# stick-breaking loop: fourth lane exchange issued with the others (counted lgkmcnt)
# baseline (speedup 1.0000x reference)
.LBB0_142:
	s_or_b64 exec, exec, s[44:45]
	v_mov_b32_e32 v108, v35
	v_mov_b32_e32 v32, v34
	v_mov_b32_e32 v106, v103
	v_mov_b32_e32 v38, v102
	v_pk_mul_f32 v[108:109], v[108:109], v[32:33]
	v_pk_mul_f32 v[106:107], v[106:107], v[38:39]
	v_mov_b32_e32 v125, v108
	v_mov_b32_e32 v124, v106
	v_mov_b32_e32 v108, v107
	v_pk_mul_f32 v[124:125], v[124:125], v[108:109]
	v_mov_b32_e32 v104, v97
	v_mov_b32_e32 v40, v96
	ds_bpermute_b32 v127, v113, v125
	ds_bpermute_b32 v126, v113, v124
	v_pk_mul_f32 v[104:105], v[104:105], v[40:41]
	v_mov_b32_e32 v100, v47
	v_pk_mul_f32 v[128:129], v[104:105], v[104:105] op_sel:[0,1] op_sel_hi:[1,0]
	ds_bpermute_b32 v102, v113, v128
	v_mov_b32_e32 v42, v46
	s_waitcnt lgkmcnt(1)
	v_pk_mul_f32 v[124:125], v[124:125], v[126:127]
	v_pk_mul_f32 v[100:101], v[100:101], v[42:43]
	v_mul_f32_e32 v106, v103, v107
	v_mov_b32_e32 v129, v124
	v_mov_b32_e32 v103, v125
	v_mul_f32_e32 v96, v100, v101
	ds_bpermute_b32 v132, v113, v96
	v_mul_f32_e32 v34, v115, v125
	s_waitcnt lgkmcnt(1)
	v_pk_mul_f32 v[124:125], v[128:129], v[102:103]
	v_mul_f32_e32 v32, v124, v125
	v_mul_f32_e32 v32, v115, v32
	v_mul_f32_e32 v100, v47, v101
	v_mul_f32_e32 v40, v115, v125
	s_waitcnt lgkmcnt(0)
	v_cndmask_b32_e32 v46, 1.0, v132, vcc
	v_mul_f32_e32 v32, v46, v32
	v_cndmask_b32_e32 v42, 1.0, v102, vcc
	v_pk_mul_f32 v[46:47], v[100:101], v[32:33] op_sel_hi:[1,0]
	v_mul_f32_e32 v104, v97, v105
	v_pk_mul_f32 v[46:47], v[98:99], v[46:47]
	v_mul_f32_e32 v43, v43, v32
	v_mul_f32_e32 v98, v122, v32
	v_mul_f32_e32 v32, v42, v40
	v_cndmask_b32_e32 v38, 1.0, v126, vcc
	v_mul_f32_e32 v97, v123, v43
	v_pk_mul_f32 v[42:43], v[104:105], v[32:33] op_sel_hi:[1,0]
	v_mul_f32_e32 v40, v41, v32
	v_pk_mul_f32 v[42:43], v[94:95], v[42:43]
	v_mul_f32_e32 v95, v121, v32
	v_mul_f32_e32 v32, v38, v34
	v_mul_f32_e32 v94, v120, v40
	v_pk_mul_f32 v[40:41], v[106:107], v[32:33] op_sel_hi:[1,0]
	v_mul_f32_e32 v34, v39, v32
	v_pk_mul_f32 v[44:45], v[44:45], v[40:41]
	v_cvt_pk_bf16_f32 v38, v46, v47
	v_cvt_pk_bf16_f32 v39, v97, v98
	v_cvt_pk_bf16_f32 v40, v42, v43
	v_cvt_pk_bf16_f32 v41, v94, v95
	v_mul_f32_e32 v43, v119, v32
	v_cndmask_b32_e32 v32, 1.0, v127, vcc
	s_waitcnt vmcnt(6)
	v_mfma_f32_32x32x16_bf16 v[0:15], v[72:75], v[38:41], v[0:15]
	v_mul_f32_e32 v32, v115, v32
	v_mul_f32_e32 v108, v35, v109
	v_mul_f32_e32 v42, v118, v34
	v_mul_f32_e64 v34, v108, v32
	v_mul_f32_e64 v35, v109, v32
	v_mul_f32_e32 v33, v33, v32
	v_pk_mul_f32 v[34:35], v[36:37], v[34:35]
	v_mul_f32_e32 v36, v116, v33
	s_waitcnt vmcnt(2)
	v_mfma_f32_32x32x16_bf16 v[16:31], v[76:79], v[38:41], v[16:31]
	v_mul_f32_e32 v37, v117, v32
	v_cvt_pk_bf16_f32 v34, v34, v35
	v_cvt_pk_bf16_f32 v35, v36, v37
	v_mul_f32_e32 v36, v96, v132
	v_cvt_pk_bf16_f32 v32, v44, v45
	v_cvt_pk_bf16_f32 v33, v42, v43
	v_mul_f32_e32 v36, v124, v36
	v_mul_f32_e32 v36, v36, v125
	v_mfma_f32_32x32x16_bf16 v[0:15], v[64:67], v[32:35], v[0:15]
	v_mul_f32_e32 v115, v115, v36
	s_mov_b32 s38, 0x2081cea
	v_cmp_gt_f32_e64 s[38:39], s38, v115
	s_cmp_eq_u64 s[38:39], exec
	v_add_co_u32_e64 v87, s[38:39], -1, v87
	s_cselect_b64 s[44:45], -1, 0
	s_waitcnt vmcnt(0)
	v_mfma_f32_32x32x16_bf16 v[16:31], v[68:71], v[32:35], v[16:31]
	s_xor_b64 s[38:39], s[38:39], -1
	s_or_b64 s[38:39], s[38:39], s[44:45]
	s_and_b64 s[38:39], exec, s[38:39]
	s_or_b64 s[42:43], s[38:39], s[42:43]
	v_subrev_u32_e32 v160, 32, v160
	s_andn2_b64 exec, exec, s[42:43]
	s_cbranch_execz .LBB0_138
